# P1 column-tile permutation per m-group: one V tile per workgroup, V tiles spread over rounds 0,2,3,5
# baseline (speedup 1.0000x reference)
;     __host__ __device__ bool next(int i, Unit& u) const {
;         const long L = (long)i * G + c; if (L >= nwg) return false;
;         int wgid = (int)L; { const int q = nwg / NXCD, r = nwg % NXCD, xcd = wgid % NXCD, off = wgid / NXCD; wgid = (xcd < r ? xcd * (q + 1) : r * (q + 1) + (xcd - r) * q) + off; }
;         const int nig = WGM * nN, gid = wgid / nig, fm = gid * WGM, gsz = (nM - fm) < WGM ? (nM - fm) : WGM;
;         u.pm = fm + ((wgid % nig) % gsz); u.pn = (wgid % nig) / gsz; return true;
;     }
; __global__ void __launch_bounds__(512, 2) hybrid_fwd(Args args) {
;     ...
;         pg8::Gemm g{XB, WIN, MTOK, NIN1, DM}; pg8::StaticOrder S; S.init(MTOK, NIN1, F.G, F.bid);
;         EpiIn E{Qb, Kb, VT, HY, SS0};
;         pg8::gemm_phase<EpiIn, pg8::StaticOrder, true, true>(F.lds, g, S, E);
.LBB0_415:
	s_cmp_lt_i32 s84, 2
	s_cselect_b64 s[2:3], -1, 0
	s_add_u32 s48, s82, 0x6000000
	s_addc_u32 s49, s83, 0
	s_add_u32 s58, s82, 0x8000000
	s_addc_u32 s59, s83, 0
	s_add_u32 s54, s82, 0xa000000
	s_addc_u32 s55, s83, 0
	s_and_b64 s[0:1], s[2:3], s[0:1]
	s_andn2_b64 vcc, exec, s[0:1]
	s_cbranch_vccnz .LBB0_626
	s_cmpk_lt_i32 s33, 0x600
	s_cselect_b64 s[2:3], -1, 0
	s_cmpk_gt_i32 s33, 0x5ff
	v_readfirstlane_b32 s12, v150
	s_cbranch_scc1 .LBB0_418
	s_ashr_i32 s4, s33, 31
	s_lshr_b32 s4, s4, 29
	s_add_i32 s4, s33, s4
	s_ashr_i32 s5, s4, 3
	s_and_b32 s4, s4, -8
	s_sub_i32 s4, s33, s4
	s_cmp_lt_i32 s4, 0
	s_movk_i32 s6, 0xc1
	s_cselect_b32 s6, s6, 0xc0
	s_mul_i32 s4, s4, s6
	s_add_i32 s4, s4, s5
	s_mul_hi_i32 s5, s4, 0x2aaaaaab
	s_lshr_b32 s6, s5, 31
	s_ashr_i32 s5, s5, 4
	s_add_i32 s5, s5, s6
	s_lshl_b32 s6, s5, 3
	s_mulk_i32 s5, 0x60
	s_sub_i32 s4, s4, s5
	s_bfe_i32 s5, s4, 0x80000
	s_bfe_u32 s5, s5, 0x3000c
	s_add_i32 s5, s4, s5
	s_bfe_i32 s7, s5, 0x80000
	s_and_b32 s5, s5, 0xf8
	s_sub_i32 s4, s4, s5
	s_sext_i32_i16 s7, s7
	s_sext_i32_i8 s4, s4
	s_add_i32 s6, s6, s4
	s_ashr_i32 s4, s7, 3
	s_mov_b32 s98, 0x76a03214
	s_lshl_b32 s99, s4, 2
	s_lshr_b32 s98, s98, s99
	s_and_b32 s4, s98, 15
	s_nop 0
	s_nop 0
	s_nop 0
	s_nop 0
	s_nop 0
	s_nop 0
	s_nop 0
	s_nop 0
	s_nop 0
	s_nop 0
	s_nop 0

;     __host__ __device__ bool next(int i, Unit& u) const {
;         const long L = (long)i * G + c; if (L >= nwg) return false;
;         int wgid = (int)L; { const int q = nwg / NXCD, r = nwg % NXCD, xcd = wgid % NXCD, off = wgid / NXCD; wgid = (xcd < r ? xcd * (q + 1) : r * (q + 1) + (xcd - r) * q) + off; }
;         const int nig = WGM * nN, gid = wgid / nig, fm = gid * WGM, gsz = (nM - fm) < WGM ? (nM - fm) : WGM;
;         u.pm = fm + ((wgid % nig) % gsz); u.pn = (wgid % nig) / gsz; return true;
;     }
.LBB0_424:
	s_add_i32 s97, s97, 1
	s_mul_i32 s2, s97, s71
	s_mul_hi_u32 s3, s97, s89
	s_add_i32 s3, s3, s2
	s_mul_i32 s2, s97, s89
	s_add_u32 s24, s2, s33
	s_addc_u32 s25, s3, s78
	v_cmp_gt_i64_e32 vcc, s[24:25], v[146:147]
	v_cmp_lt_i64_e64 s[2:3], s[24:25], v[144:145]
	s_cbranch_vccnz .LBB0_426
	s_ashr_i32 s5, s24, 31
	s_lshr_b32 s5, s5, 29
	s_add_i32 s5, s24, s5
	s_ashr_i32 s7, s5, 3
	s_and_b32 s5, s5, -8
	s_sub_i32 s5, s24, s5
	s_cmp_lt_i32 s5, 0
	s_movk_i32 s12, 0xc1
	s_cselect_b32 s12, s12, 0xc0
	s_mul_i32 s5, s5, s12
	s_add_i32 s5, s5, s7
	s_mul_hi_i32 s7, s5, 0x2aaaaaab
	s_lshr_b32 s12, s7, 31
	s_ashr_i32 s7, s7, 4
	s_add_i32 s7, s7, s12
	s_lshl_b32 s12, s7, 3
	s_sub_i32 s20, 0x80, s12
	s_min_i32 s21, s20, 8
	s_abs_i32 s20, s21
	v_cvt_f32_u32_e32 v0, s20
	s_sub_i32 s23, 0, s20
	s_mulk_i32 s7, 0x60
	s_sub_i32 s5, s5, s7
	v_rcp_iflag_f32_e32 v0, v0
	s_abs_i32 s7, s5
	s_xor_b32 s22, s5, s21
	s_ashr_i32 s22, s22, 31
	v_mul_f32_e32 v0, 0x4f7ffffe, v0
	v_cvt_u32_f32_e32 v0, v0
	s_nop 0
	v_readfirstlane_b32 s24, v0
	s_mul_i32 s23, s23, s24
	s_mul_hi_u32 s23, s24, s23
	s_add_i32 s24, s24, s23
	s_mul_hi_u32 s23, s7, s24
	s_mul_i32 s24, s23, s20
	s_sub_i32 s7, s7, s24
	s_add_i32 s25, s23, 1
	s_sub_i32 s24, s7, s20
	s_cmp_ge_u32 s7, s20
	s_cselect_b32 s23, s25, s23
	s_cselect_b32 s7, s24, s7
	s_add_i32 s24, s23, 1
	s_cmp_ge_u32 s7, s20
	s_cselect_b32 s7, s24, s23
	s_xor_b32 s7, s7, s22
	s_sub_i32 s20, s7, s22
	s_mul_i32 s7, s20, s21
	s_sub_i32 s5, s5, s7
	s_add_i32 s22, s12, s5
	s_mov_b32 s98, 0x76a03214
	s_mov_b32 s99, 0xb598
	s_bitcmp1_b32 s12, 3
	s_cselect_b32 s98, 0x76b13240, s98
	s_cselect_b32 s99, 0x5a98, s99
	s_lshl_b32 s100, s20, 2
	s_lshr_b64 s[98:99], s[98:99], s100
	s_and_b32 s20, s98, 15
	s_nop 0
	s_nop 0
	s_nop 0
	s_nop 0
